# P0 row loop: b/a projection dot products with packed f32 FMAs (128 pk_fma + 32 adds instead of 384 scalar mul/fmac/add)
# baseline (speedup 1.0000x reference)
.LBB0_40:
	s_or_b64 exec, exec, s[24:25]
	ds_read_b128 v[90:93], v48 offset:0
	ds_read_b128 v[94:97], v48 offset:1024
	ds_read_b128 v[98:101], v48 offset:2048
	ds_read_b128 v[102:105], v48 offset:3072
	ds_read_b128 v[106:109], v48 offset:4096
	ds_read_b128 v[110:113], v48 offset:5120
	ds_read_b128 v[114:117], v48 offset:6144
	ds_read_b128 v[118:121], v48 offset:7168
	ds_read_b128 v[122:125], v48 offset:8192
	ds_read_b128 v[126:129], v48 offset:9216
	ds_read_b128 v[130:133], v48 offset:10240
	ds_read_b128 v[134:137], v48 offset:11264
	s_waitcnt lgkmcnt(8)
	v_pk_fma_f32 v[156:157], v[28:29], v[90:91], 0
	v_pk_fma_f32 v[158:159], v[30:31], v[92:93], 0
	v_pk_fma_f32 v[156:157], v[24:25], v[94:95], v[156:157]
	v_pk_fma_f32 v[158:159], v[26:27], v[96:97], v[158:159]
	v_pk_fma_f32 v[156:157], v[20:21], v[98:99], v[156:157]
	v_pk_fma_f32 v[158:159], v[22:23], v[100:101], v[158:159]
	v_pk_fma_f32 v[156:157], v[16:17], v[102:103], v[156:157]
	v_pk_fma_f32 v[158:159], v[18:19], v[104:105], v[158:159]
	ds_read_b128 v[90:93], v48 offset:12288
	ds_read_b128 v[94:97], v48 offset:13312
	ds_read_b128 v[98:101], v48 offset:14336
	ds_read_b128 v[102:105], v48 offset:15360
	v_pk_add_f32 v[156:157], v[156:157], v[158:159]
	s_nop 0
	v_add_f32_e32 v50, v156, v157
	s_waitcnt lgkmcnt(8)
	v_pk_fma_f32 v[160:161], v[28:29], v[106:107], 0
	v_pk_fma_f32 v[162:163], v[30:31], v[108:109], 0
	v_pk_fma_f32 v[160:161], v[24:25], v[110:111], v[160:161]
	v_pk_fma_f32 v[162:163], v[26:27], v[112:113], v[162:163]
	v_pk_fma_f32 v[160:161], v[20:21], v[114:115], v[160:161]
	v_pk_fma_f32 v[162:163], v[22:23], v[116:117], v[162:163]
	v_pk_fma_f32 v[160:161], v[16:17], v[118:119], v[160:161]
	v_pk_fma_f32 v[162:163], v[18:19], v[120:121], v[162:163]
	ds_read_b128 v[106:109], v48 offset:16384
	ds_read_b128 v[110:113], v48 offset:17408
	ds_read_b128 v[114:117], v48 offset:18432
	ds_read_b128 v[118:121], v48 offset:19456
	v_pk_add_f32 v[160:161], v[160:161], v[162:163]
	s_nop 0
	v_add_f32_e32 v51, v160, v161
	s_waitcnt lgkmcnt(8)
	v_pk_fma_f32 v[156:157], v[28:29], v[122:123], 0
	v_pk_fma_f32 v[158:159], v[30:31], v[124:125], 0
	v_pk_fma_f32 v[156:157], v[24:25], v[126:127], v[156:157]
	v_pk_fma_f32 v[158:159], v[26:27], v[128:129], v[158:159]
	v_pk_fma_f32 v[156:157], v[20:21], v[130:131], v[156:157]
	v_pk_fma_f32 v[158:159], v[22:23], v[132:133], v[158:159]
	v_pk_fma_f32 v[156:157], v[16:17], v[134:135], v[156:157]
	v_pk_fma_f32 v[158:159], v[18:19], v[136:137], v[158:159]
	ds_read_b128 v[122:125], v48 offset:20480
	ds_read_b128 v[126:129], v48 offset:21504
	ds_read_b128 v[130:133], v48 offset:22528
	ds_read_b128 v[134:137], v48 offset:23552
	v_pk_add_f32 v[156:157], v[156:157], v[158:159]
	s_nop 0
	v_add_f32_e32 v52, v156, v157
	s_waitcnt lgkmcnt(8)
	v_pk_fma_f32 v[160:161], v[28:29], v[90:91], 0
	v_pk_fma_f32 v[162:163], v[30:31], v[92:93], 0
	v_pk_fma_f32 v[160:161], v[24:25], v[94:95], v[160:161]
	v_pk_fma_f32 v[162:163], v[26:27], v[96:97], v[162:163]
	v_pk_fma_f32 v[160:161], v[20:21], v[98:99], v[160:161]
	v_pk_fma_f32 v[162:163], v[22:23], v[100:101], v[162:163]
	v_pk_fma_f32 v[160:161], v[16:17], v[102:103], v[160:161]
	v_pk_fma_f32 v[162:163], v[18:19], v[104:105], v[162:163]
	ds_read_b128 v[90:93], v48 offset:24576
	ds_read_b128 v[94:97], v48 offset:25600
	ds_read_b128 v[98:101], v48 offset:26624
	ds_read_b128 v[102:105], v48 offset:27648
	v_pk_add_f32 v[160:161], v[160:161], v[162:163]
	s_nop 0
	v_add_f32_e32 v53, v160, v161
	s_waitcnt lgkmcnt(8)
	v_pk_fma_f32 v[156:157], v[28:29], v[106:107], 0
	v_pk_fma_f32 v[158:159], v[30:31], v[108:109], 0
	v_pk_fma_f32 v[156:157], v[24:25], v[110:111], v[156:157]
	v_pk_fma_f32 v[158:159], v[26:27], v[112:113], v[158:159]
	v_pk_fma_f32 v[156:157], v[20:21], v[114:115], v[156:157]
	v_pk_fma_f32 v[158:159], v[22:23], v[116:117], v[158:159]
	v_pk_fma_f32 v[156:157], v[16:17], v[118:119], v[156:157]
	v_pk_fma_f32 v[158:159], v[18:19], v[120:121], v[158:159]
	ds_read_b128 v[106:109], v48 offset:28672
	ds_read_b128 v[110:113], v48 offset:29696
	ds_read_b128 v[114:117], v48 offset:30720
	ds_read_b128 v[118:121], v48 offset:31744
	v_pk_add_f32 v[156:157], v[156:157], v[158:159]
	s_nop 0
	v_add_f32_e32 v70, v156, v157
	s_waitcnt lgkmcnt(8)
	v_pk_fma_f32 v[160:161], v[28:29], v[122:123], 0
	v_pk_fma_f32 v[162:163], v[30:31], v[124:125], 0
	v_pk_fma_f32 v[160:161], v[24:25], v[126:127], v[160:161]
	v_pk_fma_f32 v[162:163], v[26:27], v[128:129], v[162:163]
	v_pk_fma_f32 v[160:161], v[20:21], v[130:131], v[160:161]
	v_pk_fma_f32 v[162:163], v[22:23], v[132:133], v[162:163]
	v_pk_fma_f32 v[160:161], v[16:17], v[134:135], v[160:161]
	v_pk_fma_f32 v[162:163], v[18:19], v[136:137], v[162:163]
	ds_read_b128 v[122:125], v48 offset:32768
	ds_read_b128 v[126:129], v48 offset:33792
	ds_read_b128 v[130:133], v48 offset:34816
	ds_read_b128 v[134:137], v48 offset:35840
	v_pk_add_f32 v[160:161], v[160:161], v[162:163]
	s_nop 0
	v_add_f32_e32 v71, v160, v161
	s_waitcnt lgkmcnt(8)
	v_pk_fma_f32 v[156:157], v[28:29], v[90:91], 0
	v_pk_fma_f32 v[158:159], v[30:31], v[92:93], 0
	v_pk_fma_f32 v[156:157], v[24:25], v[94:95], v[156:157]
	v_pk_fma_f32 v[158:159], v[26:27], v[96:97], v[158:159]
	v_pk_fma_f32 v[156:157], v[20:21], v[98:99], v[156:157]
	v_pk_fma_f32 v[158:159], v[22:23], v[100:101], v[158:159]
	v_pk_fma_f32 v[156:157], v[16:17], v[102:103], v[156:157]
	v_pk_fma_f32 v[158:159], v[18:19], v[104:105], v[158:159]
	ds_read_b128 v[90:93], v48 offset:36864
	ds_read_b128 v[94:97], v48 offset:37888
	ds_read_b128 v[98:101], v48 offset:38912
	ds_read_b128 v[102:105], v48 offset:39936
	v_pk_add_f32 v[156:157], v[156:157], v[158:159]
	s_nop 0
	v_add_f32_e32 v72, v156, v157
	s_waitcnt lgkmcnt(8)
	v_pk_fma_f32 v[160:161], v[28:29], v[106:107], 0
	v_pk_fma_f32 v[162:163], v[30:31], v[108:109], 0
	v_pk_fma_f32 v[160:161], v[24:25], v[110:111], v[160:161]
	v_pk_fma_f32 v[162:163], v[26:27], v[112:113], v[162:163]
	v_pk_fma_f32 v[160:161], v[20:21], v[114:115], v[160:161]
	v_pk_fma_f32 v[162:163], v[22:23], v[116:117], v[162:163]
	v_pk_fma_f32 v[160:161], v[16:17], v[118:119], v[160:161]
	v_pk_fma_f32 v[162:163], v[18:19], v[120:121], v[162:163]
	ds_read_b128 v[106:109], v48 offset:40960
	ds_read_b128 v[110:113], v48 offset:41984
	ds_read_b128 v[114:117], v48 offset:43008
	ds_read_b128 v[118:121], v48 offset:44032
	v_pk_add_f32 v[160:161], v[160:161], v[162:163]
	s_nop 0
	v_add_f32_e32 v73, v160, v161
	s_waitcnt lgkmcnt(8)
	v_pk_fma_f32 v[156:157], v[28:29], v[122:123], 0
	v_pk_fma_f32 v[158:159], v[30:31], v[124:125], 0
	v_pk_fma_f32 v[156:157], v[24:25], v[126:127], v[156:157]
	v_pk_fma_f32 v[158:159], v[26:27], v[128:129], v[158:159]
	v_pk_fma_f32 v[156:157], v[20:21], v[130:131], v[156:157]
	v_pk_fma_f32 v[158:159], v[22:23], v[132:133], v[158:159]
	v_pk_fma_f32 v[156:157], v[16:17], v[134:135], v[156:157]
	v_pk_fma_f32 v[158:159], v[18:19], v[136:137], v[158:159]
	ds_read_b128 v[122:125], v48 offset:45056
	ds_read_b128 v[126:129], v48 offset:46080
	ds_read_b128 v[130:133], v48 offset:47104
	ds_read_b128 v[134:137], v48 offset:48128
	v_pk_add_f32 v[156:157], v[156:157], v[158:159]
	s_nop 0
	v_add_f32_e32 v74, v156, v157
	s_waitcnt lgkmcnt(8)
	v_pk_fma_f32 v[160:161], v[28:29], v[90:91], 0
	v_pk_fma_f32 v[162:163], v[30:31], v[92:93], 0
	v_pk_fma_f32 v[160:161], v[24:25], v[94:95], v[160:161]
	v_pk_fma_f32 v[162:163], v[26:27], v[96:97], v[162:163]
	v_pk_fma_f32 v[160:161], v[20:21], v[98:99], v[160:161]
	v_pk_fma_f32 v[162:163], v[22:23], v[100:101], v[162:163]
	v_pk_fma_f32 v[160:161], v[16:17], v[102:103], v[160:161]
	v_pk_fma_f32 v[162:163], v[18:19], v[104:105], v[162:163]
	ds_read_b128 v[90:93], v48 offset:49152
	ds_read_b128 v[94:97], v48 offset:50176
	ds_read_b128 v[98:101], v48 offset:51200
	ds_read_b128 v[102:105], v48 offset:52224
	v_pk_add_f32 v[160:161], v[160:161], v[162:163]
	s_nop 0
	v_add_f32_e32 v75, v160, v161
	s_waitcnt lgkmcnt(8)
	v_pk_fma_f32 v[156:157], v[28:29], v[106:107], 0
	v_pk_fma_f32 v[158:159], v[30:31], v[108:109], 0
	v_pk_fma_f32 v[156:157], v[24:25], v[110:111], v[156:157]
	v_pk_fma_f32 v[158:159], v[26:27], v[112:113], v[158:159]
	v_pk_fma_f32 v[156:157], v[20:21], v[114:115], v[156:157]
	v_pk_fma_f32 v[158:159], v[22:23], v[116:117], v[158:159]
	v_pk_fma_f32 v[156:157], v[16:17], v[118:119], v[156:157]
	v_pk_fma_f32 v[158:159], v[18:19], v[120:121], v[158:159]
	ds_read_b128 v[106:109], v48 offset:53248
	ds_read_b128 v[110:113], v48 offset:54272
	ds_read_b128 v[114:117], v48 offset:55296
	ds_read_b128 v[118:121], v48 offset:56320
	v_pk_add_f32 v[156:157], v[156:157], v[158:159]
	s_nop 0
	v_add_f32_e32 v76, v156, v157
	s_waitcnt lgkmcnt(8)
	v_pk_fma_f32 v[160:161], v[28:29], v[122:123], 0
	v_pk_fma_f32 v[162:163], v[30:31], v[124:125], 0
	v_pk_fma_f32 v[160:161], v[24:25], v[126:127], v[160:161]
	v_pk_fma_f32 v[162:163], v[26:27], v[128:129], v[162:163]
	v_pk_fma_f32 v[160:161], v[20:21], v[130:131], v[160:161]
	v_pk_fma_f32 v[162:163], v[22:23], v[132:133], v[162:163]
	v_pk_fma_f32 v[160:161], v[16:17], v[134:135], v[160:161]
	v_pk_fma_f32 v[162:163], v[18:19], v[136:137], v[162:163]
	ds_read_b128 v[122:125], v48 offset:57344
	ds_read_b128 v[126:129], v48 offset:58368
	ds_read_b128 v[130:133], v48 offset:59392
	ds_read_b128 v[134:137], v48 offset:60416
	v_pk_add_f32 v[160:161], v[160:161], v[162:163]
	s_nop 0
	v_add_f32_e32 v77, v160, v161
	s_waitcnt lgkmcnt(8)
	v_pk_fma_f32 v[156:157], v[28:29], v[90:91], 0
	v_pk_fma_f32 v[158:159], v[30:31], v[92:93], 0
	v_pk_fma_f32 v[156:157], v[24:25], v[94:95], v[156:157]
	v_pk_fma_f32 v[158:159], v[26:27], v[96:97], v[158:159]
	v_pk_fma_f32 v[156:157], v[20:21], v[98:99], v[156:157]
	v_pk_fma_f32 v[158:159], v[22:23], v[100:101], v[158:159]
	v_pk_fma_f32 v[156:157], v[16:17], v[102:103], v[156:157]
	v_pk_fma_f32 v[158:159], v[18:19], v[104:105], v[158:159]
	ds_read_b128 v[90:93], v48 offset:61440
	ds_read_b128 v[94:97], v48 offset:62464
	ds_read_b128 v[98:101], v48 offset:63488
	ds_read_b128 v[102:105], v48 offset:64512
	v_pk_add_f32 v[156:157], v[156:157], v[158:159]
	s_nop 0
	v_add_f32_e32 v78, v156, v157
	s_waitcnt lgkmcnt(8)
	v_pk_fma_f32 v[160:161], v[28:29], v[106:107], 0
	v_pk_fma_f32 v[162:163], v[30:31], v[108:109], 0
	v_pk_fma_f32 v[160:161], v[24:25], v[110:111], v[160:161]
	v_pk_fma_f32 v[162:163], v[26:27], v[112:113], v[162:163]
	v_pk_fma_f32 v[160:161], v[20:21], v[114:115], v[160:161]
	v_pk_fma_f32 v[162:163], v[22:23], v[116:117], v[162:163]
	v_pk_fma_f32 v[160:161], v[16:17], v[118:119], v[160:161]
	v_pk_fma_f32 v[162:163], v[18:19], v[120:121], v[162:163]
	v_pk_add_f32 v[160:161], v[160:161], v[162:163]
	s_nop 0
	v_add_f32_e32 v79, v160, v161
	s_waitcnt lgkmcnt(4)
	v_pk_fma_f32 v[156:157], v[28:29], v[122:123], 0
	v_pk_fma_f32 v[158:159], v[30:31], v[124:125], 0
	v_pk_fma_f32 v[156:157], v[24:25], v[126:127], v[156:157]
	v_pk_fma_f32 v[158:159], v[26:27], v[128:129], v[158:159]
	v_pk_fma_f32 v[156:157], v[20:21], v[130:131], v[156:157]
	v_pk_fma_f32 v[158:159], v[22:23], v[132:133], v[158:159]
	v_pk_fma_f32 v[156:157], v[16:17], v[134:135], v[156:157]
	v_pk_fma_f32 v[158:159], v[18:19], v[136:137], v[158:159]
	v_pk_add_f32 v[156:157], v[156:157], v[158:159]
	s_nop 0
	v_add_f32_e32 v80, v156, v157
	s_waitcnt lgkmcnt(0)
	v_pk_fma_f32 v[160:161], v[28:29], v[90:91], 0
	v_pk_fma_f32 v[162:163], v[30:31], v[92:93], 0
	v_pk_fma_f32 v[160:161], v[24:25], v[94:95], v[160:161]
	v_pk_fma_f32 v[162:163], v[26:27], v[96:97], v[162:163]
	v_pk_fma_f32 v[160:161], v[20:21], v[98:99], v[160:161]
	v_pk_fma_f32 v[162:163], v[22:23], v[100:101], v[162:163]
	v_pk_fma_f32 v[160:161], v[16:17], v[102:103], v[160:161]
	v_pk_fma_f32 v[162:163], v[18:19], v[104:105], v[162:163]
	v_pk_add_f32 v[160:161], v[160:161], v[162:163]
	s_nop 0
	v_add_f32_e32 v16, v160, v161
	v_cndmask_b32_e64 v18, v50, v51, s[4:5]
	ds_bpermute_b32 v18, v42, v18
	v_cndmask_b32_e64 v19, v52, v53, s[4:5]
	ds_bpermute_b32 v19, v42, v19
	v_cndmask_b32_e64 v20, v70, v71, s[4:5]
	ds_bpermute_b32 v20, v42, v20
	v_cndmask_b32_e64 v21, v72, v73, s[4:5]
	ds_bpermute_b32 v21, v42, v21
	v_cndmask_b32_e64 v22, v74, v75, s[4:5]
	v_cndmask_b32_e64 v17, v51, v50, s[4:5]
	ds_bpermute_b32 v22, v42, v22
	v_cndmask_b32_e64 v23, v76, v77, s[4:5]
	s_waitcnt lgkmcnt(4)
	v_add_f32_e32 v17, v17, v18
	v_cndmask_b32_e64 v18, v53, v52, s[4:5]
	ds_bpermute_b32 v23, v42, v23
	v_cndmask_b32_e64 v24, v78, v79, s[4:5]
	v_cndmask_b32_e64 v25, v80, v16, s[4:5]
	s_waitcnt lgkmcnt(4)
	v_add_f32_e32 v18, v18, v19
	v_cndmask_b32_e64 v19, v71, v70, s[4:5]
	ds_bpermute_b32 v24, v42, v24
	ds_bpermute_b32 v25, v42, v25
	s_waitcnt lgkmcnt(5)
	v_add_f32_e32 v19, v19, v20
	v_cndmask_b32_e64 v20, v73, v72, s[4:5]
	s_waitcnt lgkmcnt(4)
	v_add_f32_e32 v20, v20, v21
	v_cndmask_b32_e64 v21, v75, v74, s[4:5]
	s_waitcnt lgkmcnt(3)
	v_add_f32_e32 v21, v21, v22
	v_cndmask_b32_e64 v22, v77, v76, s[4:5]
	s_waitcnt lgkmcnt(2)
	v_add_f32_e32 v22, v22, v23
	v_cndmask_b32_e64 v23, v79, v78, s[4:5]
	v_cndmask_b32_e64 v16, v16, v80, s[4:5]
	v_cndmask_b32_e64 v26, v17, v18, s[6:7]
	s_waitcnt lgkmcnt(1)
	v_add_f32_e32 v23, v23, v24
	s_waitcnt lgkmcnt(0)
	v_add_f32_e32 v16, v16, v25
	v_cndmask_b32_e64 v17, v18, v17, s[6:7]
	v_cndmask_b32_e64 v18, v20, v19, s[6:7]
	v_cndmask_b32_e64 v19, v19, v20, s[6:7]
	ds_bpermute_b32 v19, v43, v19
	v_cndmask_b32_e64 v20, v21, v22, s[6:7]
	v_cndmask_b32_e64 v24, v23, v16, s[6:7]
	ds_bpermute_b32 v26, v43, v26
	ds_bpermute_b32 v20, v43, v20
	ds_bpermute_b32 v24, v43, v24
	s_waitcnt lgkmcnt(3)
	v_add_f32_e32 v18, v18, v19
	v_cndmask_b32_e64 v19, v22, v21, s[6:7]
	v_cndmask_b32_e64 v16, v16, v23, s[6:7]
	s_waitcnt lgkmcnt(2)
	v_add_f32_e32 v17, v17, v26
	s_waitcnt lgkmcnt(1)
	v_add_f32_e32 v19, v19, v20
	s_waitcnt lgkmcnt(0)
	v_add_f32_e32 v16, v16, v24
	v_cndmask_b32_e64 v20, v17, v18, s[8:9]
	v_cndmask_b32_e64 v21, v19, v16, s[8:9]
	ds_bpermute_b32 v20, v44, v20
	ds_bpermute_b32 v21, v44, v21
	v_cndmask_b32_e64 v17, v18, v17, s[8:9]
	v_cndmask_b32_e64 v16, v16, v19, s[8:9]
	s_waitcnt lgkmcnt(1)
	v_add_f32_e32 v17, v17, v20
	s_waitcnt lgkmcnt(0)
	v_add_f32_e32 v16, v16, v21
	v_cndmask_b32_e64 v18, v17, v16, s[10:11]
	ds_bpermute_b32 v18, v45, v18
	v_cndmask_b32_e64 v16, v16, v17, s[10:11]
	s_waitcnt lgkmcnt(0)
	v_add_f32_e32 v16, v16, v18
	ds_bpermute_b32 v17, v46, v16
	s_waitcnt lgkmcnt(0)
	v_add_f32_e32 v16, v16, v17
	ds_bpermute_b32 v17, v47, v16
	s_and_saveexec_b64 s[24:25], s[12:13]
	s_cbranch_execz .LBB0_37
	v_fmamk_f32 v18, v49, 0x3a800000, v33
	v_mul_f32_e32 v19, 0x4b800000, v18
	v_cmp_gt_f32_e32 vcc, s28, v18
	s_waitcnt lgkmcnt(0)
	v_add_f32_e32 v16, v16, v17
	v_cndmask_b32_e32 v18, v18, v19, vcc
	v_rsq_f32_e32 v18, v18
	s_nop 0
	v_mul_f32_e32 v17, 0x45800000, v18
	v_cndmask_b32_e32 v17, v18, v17, vcc
	v_mul_f32_e32 v18, v17, v16
	v_add_co_u32_e32 v16, vcc, 0x400000, v40
	s_nop 1
	v_addc_co_u32_e32 v17, vcc, 0, v41, vcc
	global_store_dword v[16:17], v18, off
	s_branch .LBB0_37
